# ml_seq: waves 0-3 defer their state-transform chains to the next chunk's staging phase
# speedup vs baseline: 1.0084x; 1.0084x over previous
.Lmlq_noearly:
	v_and_b32_e32 v119, 0xffff0000, v142
	v_lshlrev_b32_e32 v118, 16, v142
	v_lshlrev_b32_e32 v120, 16, v143
	s_waitcnt lgkmcnt(9)
	v_mul_f32_e32 v106, v106, v119
	v_fmac_f32_e32 v106, v102, v118
	v_and_b32_e32 v121, 0xffff0000, v143
	v_fmac_f32_e32 v106, v110, v120
	v_fmac_f32_e32 v106, v114, v121
	v_cvt_pk_bf16_f32 v102, v106, s0
	ds_write_b16 v165, v102
	v_mul_f32_e32 v102, v153, v106
	v_cvt_pk_bf16_f32 v102, v102, s0
	ds_write_b16 v166, v102
	v_mul_f32_e32 v102, v107, v119
	v_fmac_f32_e32 v102, v103, v118
	v_fmac_f32_e32 v102, v111, v120
	v_fmac_f32_e32 v102, v115, v121
	v_cvt_pk_bf16_f32 v103, v102, s0
	v_mul_f32_e32 v102, v153, v102
	v_cvt_pk_bf16_f32 v102, v102, s0
	ds_write_b16 v168, v102
	v_mul_f32_e32 v102, v108, v119
	v_fmac_f32_e32 v102, v104, v118
	v_fmac_f32_e32 v102, v112, v120
	v_fmac_f32_e32 v102, v116, v121
	ds_write_b16 v167, v103
	v_cvt_pk_bf16_f32 v103, v102, s0
	v_mul_f32_e32 v102, v153, v102
	v_cvt_pk_bf16_f32 v102, v102, s0
	ds_write_b16 v170, v102
	v_mul_f32_e32 v102, v109, v119
	v_fmac_f32_e32 v102, v105, v118
	v_fmac_f32_e32 v102, v113, v120
	v_fmac_f32_e32 v102, v117, v121
	ds_write_b16 v169, v103
	v_cvt_pk_bf16_f32 v103, v102, s0
	v_mul_f32_e32 v102, v153, v102
	v_cvt_pk_bf16_f32 v102, v102, s0
	ds_write_b16 v171, v103
	ds_write_b16 v172, v102
	s_cmp_eq_u32 s30, 0
	s_cbranch_scc1 .Lmlq_nochains_t0
	s_cmp_eq_u64 s[6:7], 0
	s_cbranch_scc1 .Lmlq_nochains_t0
	s_and_b32 s24, s30, 1
	s_mul_i32 s25, s24, 0x8200
	s_mulk_i32 s24, 0x440
	v_add_u32_e32 v122, s25, v176
	v_add_u32_e32 v123, s24, v164
	v_cvt_pk_bf16_f32 v194, v66, v67
	v_cvt_pk_bf16_f32 v195, v68, v69
	v_mov_b32_e32 v196, v0
	v_mov_b32_e32 v197, v0
	v_cvt_pk_bf16_f32 v198, v62, v63
	v_cvt_pk_bf16_f32 v199, v64, v65
	v_mov_b32_e32 v200, v0
	v_mov_b32_e32 v201, v0
	v_cvt_pk_bf16_f32 v202, v74, v75
	v_cvt_pk_bf16_f32 v203, v76, v77
	v_mov_b32_e32 v204, v0
	v_mov_b32_e32 v205, v0
	v_cvt_pk_bf16_f32 v206, v58, v59
	v_cvt_pk_bf16_f32 v207, v60, v61
	v_mov_b32_e32 v208, v0
	v_mov_b32_e32 v209, v0
	v_cvt_pk_bf16_f32 v210, v54, v55
	v_cvt_pk_bf16_f32 v211, v56, v57
	v_mov_b32_e32 v212, v0
	v_mov_b32_e32 v213, v0
	v_cvt_pk_bf16_f32 v214, v70, v71
	v_cvt_pk_bf16_f32 v215, v72, v73
	v_mov_b32_e32 v216, v0
	v_mov_b32_e32 v217, v0
	v_cvt_pk_bf16_f32 v218, v82, v83
	v_cvt_pk_bf16_f32 v219, v84, v85
	v_mov_b32_e32 v220, v0
	v_mov_b32_e32 v221, v0
	v_cvt_pk_bf16_f32 v222, v86, v87
	v_cvt_pk_bf16_f32 v223, v88, v89
	v_mov_b32_e32 v224, v0
	v_mov_b32_e32 v225, v0
	v_cvt_pk_bf16_f32 v124, v78, v79
	v_cvt_pk_bf16_f32 v125, v80, v81
	v_mov_b32_e32 v126, v0
	v_mov_b32_e32 v127, v0
	v_cvt_pk_bf16_f32 v128, v94, v95
	v_cvt_pk_bf16_f32 v129, v96, v97
	v_mov_b32_e32 v130, v0
	v_mov_b32_e32 v131, v0
	v_cvt_pk_bf16_f32 v132, v98, v99
	v_cvt_pk_bf16_f32 v133, v100, v101
	v_mov_b32_e32 v134, v0
	v_mov_b32_e32 v135, v0
	v_cvt_pk_bf16_f32 v136, v90, v91
	v_cvt_pk_bf16_f32 v137, v92, v93
	v_mov_b32_e32 v138, v0
	v_mov_b32_e32 v139, v0
	v_mfma_f32_16x16x32_bf16 v[194:197], v[30:33], v[194:197], 0
	v_mfma_f32_16x16x32_bf16 v[198:201], v[30:33], v[198:201], 0
	v_mfma_f32_16x16x32_bf16 v[202:205], v[30:33], v[202:205], 0
	v_mfma_f32_16x16x32_bf16 v[206:209], v[42:45], v[206:209], 0
	v_mfma_f32_16x16x32_bf16 v[210:213], v[42:45], v[210:213], 0
	v_mfma_f32_16x16x32_bf16 v[214:217], v[42:45], v[214:217], 0
	v_mfma_f32_16x16x32_bf16 v[218:221], v[46:49], v[218:221], 0
	v_mfma_f32_16x16x32_bf16 v[222:225], v[46:49], v[222:225], 0
	v_mfma_f32_16x16x32_bf16 v[124:127], v[46:49], v[124:127], 0
	v_mfma_f32_16x16x32_bf16 v[128:131], v[50:53], v[128:131], 0
	v_mfma_f32_16x16x32_bf16 v[132:135], v[50:53], v[132:135], 0
	v_mfma_f32_16x16x32_bf16 v[136:139], v[50:53], v[136:139], 0
	v_cvt_pk_bf16_f32 v194, v194, v195
	v_cvt_pk_bf16_f32 v195, v196, v197
	ds_write_b64 v122, v[194:195]
	v_cvt_pk_bf16_f32 v198, v198, v199
	v_cvt_pk_bf16_f32 v199, v200, v201
	ds_write_b64 v122, v[198:199] offset:16640
	v_cvt_pk_bf16_f32 v202, v202, v203
	v_cvt_pk_bf16_f32 v203, v204, v205
	v_cvt_pk_bf16_f32 v206, v206, v207
	v_cvt_pk_bf16_f32 v207, v208, v209
	ds_write_b64 v122, v[206:207] offset:32
	v_cvt_pk_bf16_f32 v210, v210, v211
	v_cvt_pk_bf16_f32 v211, v212, v213
	ds_write_b64 v122, v[210:211] offset:16672
	v_cvt_pk_bf16_f32 v214, v214, v215
	v_cvt_pk_bf16_f32 v215, v216, v217
	v_cvt_pk_bf16_f32 v218, v218, v219
	v_cvt_pk_bf16_f32 v219, v220, v221
	ds_write_b64 v122, v[218:219] offset:64
	v_cvt_pk_bf16_f32 v222, v222, v223
	v_cvt_pk_bf16_f32 v223, v224, v225
	ds_write_b64 v122, v[222:223] offset:16704
	v_cvt_pk_bf16_f32 v124, v124, v125
	v_cvt_pk_bf16_f32 v125, v126, v127
	v_cvt_pk_bf16_f32 v128, v128, v129
	v_cvt_pk_bf16_f32 v129, v130, v131
	ds_write_b64 v122, v[128:129] offset:96
	v_cvt_pk_bf16_f32 v132, v132, v133
	v_cvt_pk_bf16_f32 v133, v134, v135
	ds_write_b64 v122, v[132:133] offset:16736
	v_cvt_pk_bf16_f32 v136, v136, v137
	v_cvt_pk_bf16_f32 v137, v138, v139
	s_and_saveexec_b64 s[24:25], s[8:9]
	ds_write_b64 v123, v[202:203]
	ds_write_b64 v123, v[214:215] offset:32
	ds_write_b64 v123, v[124:125] offset:64
	ds_write_b64 v123, v[136:137] offset:96
	s_or_b64 exec, exec, s[24:25]
.Lmlq_nochains_t0:
	s_cmpk_eq_i32 s30, 0x7f
	s_cbranch_scc1 .Lmlq_nolate
	global_load_dword v153, v[228:229], off offset:256
	global_load_dwordx2 v[142:143], v[230:231], off

.LBB0_805:
	s_or_b64 exec, exec, s[22:23]
	v_readlane_b32 s22, v255, 18
	v_mov_b32_e32 v108, 0
	v_mov_b32_e32 v109, 0
	v_mov_b32_e32 v102, s22
	ds_read_b32 v116, v102
	ds_read_b128 v[112:115], v162
	ds_read_b128 v[104:107], v162 offset:2304
	v_mov_b32_e32 v102, 0
	v_mov_b32_e32 v110, 0
	v_mov_b32_e32 v111, 0
	s_and_saveexec_b64 s[22:23], s[8:9]
	ds_read_b128 v[108:111], v163
	s_or_b64 exec, exec, s[22:23]
	s_waitcnt lgkmcnt(2)
	v_pk_mul_f32 v[134:135], v[54:55], v[116:117] op_sel_hi:[1,0]
	v_pk_mul_f32 v[188:189], v[72:73], v[116:117] op_sel_hi:[1,0]
	v_pk_mul_f32 v[186:187], v[70:71], v[116:117] op_sel_hi:[1,0]
	v_pk_mul_f32 v[72:73], v[88:89], v[116:117] op_sel_hi:[1,0]
	v_pk_mul_f32 v[70:71], v[86:87], v[116:117] op_sel_hi:[1,0]
	v_pk_mul_f32 v[54:55], v[98:99], v[116:117] op_sel_hi:[1,0]
	ds_read_b64_tr_b16 v[88:89], v193 offset:4160
	ds_read_b64_tr_b16 v[86:87], v193
	ds_read_b64_tr_b16 v[98:99], v193 offset:32
	v_pk_mul_f32 v[120:121], v[68:69], v[116:117] op_sel_hi:[1,0]
	v_pk_mul_f32 v[118:119], v[66:67], v[116:117] op_sel_hi:[1,0]
	v_pk_mul_f32 v[124:125], v[64:65], v[116:117] op_sel_hi:[1,0]
	v_pk_mul_f32 v[122:123], v[62:63], v[116:117] op_sel_hi:[1,0]
	v_pk_mul_f32 v[128:129], v[76:77], v[116:117] op_sel_hi:[1,0]
	v_pk_mul_f32 v[126:127], v[74:75], v[116:117] op_sel_hi:[1,0]
	v_pk_mul_f32 v[136:137], v[56:57], v[116:117] op_sel_hi:[1,0]
	v_pk_mul_f32 v[68:69], v[84:85], v[116:117] op_sel_hi:[1,0]
	v_pk_mul_f32 v[66:67], v[82:83], v[116:117] op_sel_hi:[1,0]
	v_pk_mul_f32 v[76:77], v[80:81], v[116:117] op_sel_hi:[1,0]
	v_pk_mul_f32 v[74:75], v[78:79], v[116:117] op_sel_hi:[1,0]
	v_pk_mul_f32 v[56:57], v[100:101], v[116:117] op_sel_hi:[1,0]
	s_waitcnt lgkmcnt(1)
	v_mfma_f32_16x16x32_bf16 v[78:81], v[86:89], v[112:115], v[118:121]
	ds_read_b64_tr_b16 v[100:101], v193 offset:4192
	v_pk_mul_f32 v[132:133], v[60:61], v[116:117] op_sel_hi:[1,0]
	v_pk_mul_f32 v[130:131], v[58:59], v[116:117] op_sel_hi:[1,0]
	v_mfma_f32_16x16x32_bf16 v[82:85], v[86:89], v[104:107], v[122:125]
	v_mul_f32_e64 v64, v96, v116
	v_mul_f32_e64 v65, v97, v116
	v_pk_mul_f32 v[62:63], v[94:95], v[116:117] op_sel_hi:[1,0]
	v_pk_mul_f32 v[60:61], v[92:93], v[116:117] op_sel_hi:[1,0]
	v_mfma_f32_16x16x32_bf16 v[86:89], v[86:89], v[108:111], v[126:129]
	ds_read_b64_tr_b16 v[124:125], v193 offset:64
	s_nop 1
	ds_read_b64_tr_b16 v[126:127], v193 offset:4224
	v_pk_mul_f32 v[58:59], v[90:91], v[116:117] op_sel_hi:[1,0]
	v_mov_b32_e32 v103, 0
	s_waitcnt lgkmcnt(0)
	v_mfma_f32_16x16x32_bf16 v[116:119], v[124:127], v[112:115], v[66:69]
	s_nop 2
	ds_read_b64_tr_b16 v[66:67], v193 offset:96
	ds_read_b64_tr_b16 v[68:69], v193 offset:4256
	v_mfma_f32_16x16x32_bf16 v[90:93], v[98:101], v[112:115], v[130:133]
	v_mfma_f32_16x16x32_bf16 v[94:97], v[98:101], v[104:107], v[134:137]
	s_nop 2
	ds_read_b128 v[132:135], v162 offset:64
	ds_read_b128 v[136:139], v162 offset:2368
	v_mfma_f32_16x16x32_bf16 v[98:101], v[98:101], v[108:111], v[186:189]
	v_mfma_f32_16x16x32_bf16 v[120:123], v[124:127], v[104:107], v[70:73]
	v_mfma_f32_16x16x32_bf16 v[124:127], v[124:127], v[108:111], v[74:77]
	s_waitcnt lgkmcnt(2)
	v_mfma_f32_16x16x32_bf16 v[112:115], v[66:69], v[112:115], v[62:65]
	v_mfma_f32_16x16x32_bf16 v[128:131], v[66:69], v[104:107], v[54:57]
	v_mov_b32_e32 v104, 0
	v_mov_b32_e32 v105, 0
	v_mfma_f32_16x16x32_bf16 v[106:109], v[66:69], v[108:111], v[58:61]
	s_and_saveexec_b64 s[22:23], s[8:9]
	ds_read_b128 v[102:105], v163 offset:64
	s_or_b64 exec, exec, s[22:23]
	ds_read_b64_tr_b16 v[56:57], v193 offset:37440
	ds_read_b64_tr_b16 v[54:55], v193 offset:33280
	ds_read_b64_tr_b16 v[70:71], v193 offset:33312
	ds_read_b64_tr_b16 v[72:73], v193 offset:37472
	s_and_b32 s22, s29, 1
	s_mul_i32 s23, s22, 0x8200
	s_waitcnt lgkmcnt(2)
	v_mfma_f32_16x16x32_bf16 v[66:69], v[54:57], v[132:135], v[78:81]
	s_nop 2
	ds_read_b64_tr_b16 v[78:79], v193 offset:33344
	ds_read_b64_tr_b16 v[80:81], v193 offset:37504
	s_mulk_i32 s22, 0x440
	v_mfma_f32_16x16x32_bf16 v[62:65], v[54:57], v[136:139], v[82:85]
	s_waitcnt lgkmcnt(2)
	v_mfma_f32_16x16x32_bf16 v[58:61], v[70:73], v[132:135], v[90:93]
	s_nop 2
	ds_read_b64_tr_b16 v[90:91], v193 offset:33376
	ds_read_b64_tr_b16 v[92:93], v193 offset:37536
	v_mfma_f32_16x16x32_bf16 v[74:77], v[54:57], v[102:105], v[86:89]
	v_mfma_f32_16x16x32_bf16 v[54:57], v[70:73], v[136:139], v[94:97]
	v_mfma_f32_16x16x32_bf16 v[70:73], v[70:73], v[102:105], v[98:101]
	s_waitcnt lgkmcnt(2)
	v_mfma_f32_16x16x32_bf16 v[82:85], v[78:81], v[132:135], v[116:119]
	v_mfma_f32_16x16x32_bf16 v[86:89], v[78:81], v[136:139], v[120:123]
	v_mfma_f32_16x16x32_bf16 v[78:81], v[78:81], v[102:105], v[124:127]
	s_waitcnt lgkmcnt(0)
	v_mfma_f32_16x16x32_bf16 v[94:97], v[90:93], v[132:135], v[112:115]
	v_mfma_f32_16x16x32_bf16 v[98:101], v[90:93], v[136:139], v[128:131]
	v_mfma_f32_16x16x32_bf16 v[90:93], v[90:93], v[102:105], v[106:109]
	s_cmp_lg_u64 s[6:7], 0
	s_cbranch_scc0 .Lmlq_dochains
	s_mov_b64 s[22:23], exec
	s_branch .LBB0_790
.Lmlq_dochains:
	v_cvt_pk_bf16_f32 v194, v66, v67
	v_cvt_pk_bf16_f32 v195, v68, v69
	v_mov_b32_e32 v196, v0
	v_mov_b32_e32 v197, v0
	v_cvt_pk_bf16_f32 v198, v62, v63
	v_cvt_pk_bf16_f32 v199, v64, v65
	v_mov_b32_e32 v200, v0
	v_mov_b32_e32 v201, v0
	v_cvt_pk_bf16_f32 v202, v74, v75
	v_cvt_pk_bf16_f32 v203, v76, v77
	v_mov_b32_e32 v204, v0
	v_mov_b32_e32 v205, v0
	v_cvt_pk_bf16_f32 v206, v58, v59
	v_cvt_pk_bf16_f32 v207, v60, v61
	v_mov_b32_e32 v208, v0
	v_mov_b32_e32 v209, v0
	v_cvt_pk_bf16_f32 v210, v54, v55
	v_cvt_pk_bf16_f32 v211, v56, v57
	v_mov_b32_e32 v212, v0
	v_mov_b32_e32 v213, v0
	v_cvt_pk_bf16_f32 v214, v70, v71
	v_cvt_pk_bf16_f32 v215, v72, v73
	v_mov_b32_e32 v216, v0
	v_mov_b32_e32 v217, v0
	v_cvt_pk_bf16_f32 v218, v82, v83
	v_cvt_pk_bf16_f32 v219, v84, v85
	v_mov_b32_e32 v220, v0
	v_mov_b32_e32 v221, v0
	v_cvt_pk_bf16_f32 v222, v86, v87
	v_cvt_pk_bf16_f32 v223, v88, v89
	v_mov_b32_e32 v224, v0
	v_mov_b32_e32 v225, v0
	v_cvt_pk_bf16_f32 v226, v78, v79
	v_cvt_pk_bf16_f32 v227, v80, v81
	v_mov_b32_e32 v228, v0
	v_mov_b32_e32 v229, v0
	v_cvt_pk_bf16_f32 v230, v94, v95
	v_cvt_pk_bf16_f32 v231, v96, v97
	v_mov_b32_e32 v232, v0
	v_mov_b32_e32 v233, v0
	v_cvt_pk_bf16_f32 v132, v98, v99
	v_cvt_pk_bf16_f32 v133, v100, v101
	v_mov_b32_e32 v134, v0
	v_mov_b32_e32 v135, v0
	v_cvt_pk_bf16_f32 v136, v90, v91
	v_cvt_pk_bf16_f32 v137, v92, v93
	v_mov_b32_e32 v138, v0
	v_mov_b32_e32 v139, v0
	v_add_u32_e32 v106, s23, v176
	v_add_u32_e32 v107, s22, v164
	v_mfma_f32_16x16x32_bf16 v[194:197], v[30:33], v[194:197], 0
	v_mfma_f32_16x16x32_bf16 v[198:201], v[30:33], v[198:201], 0
	v_mfma_f32_16x16x32_bf16 v[202:205], v[30:33], v[202:205], 0
	v_mfma_f32_16x16x32_bf16 v[206:209], v[42:45], v[206:209], 0
	v_mfma_f32_16x16x32_bf16 v[210:213], v[42:45], v[210:213], 0
	v_mfma_f32_16x16x32_bf16 v[214:217], v[42:45], v[214:217], 0
	v_mfma_f32_16x16x32_bf16 v[218:221], v[46:49], v[218:221], 0
	v_mfma_f32_16x16x32_bf16 v[222:225], v[46:49], v[222:225], 0
	v_mfma_f32_16x16x32_bf16 v[226:229], v[46:49], v[226:229], 0
	v_mfma_f32_16x16x32_bf16 v[230:233], v[50:53], v[230:233], 0
	v_mfma_f32_16x16x32_bf16 v[132:135], v[50:53], v[132:135], 0
	v_mfma_f32_16x16x32_bf16 v[136:139], v[50:53], v[136:139], 0
	v_cvt_pk_bf16_f32 v194, v194, v195
	v_cvt_pk_bf16_f32 v195, v196, v197
	ds_write_b64 v106, v[194:195]
	v_cvt_pk_bf16_f32 v198, v198, v199
	v_cvt_pk_bf16_f32 v199, v200, v201
	ds_write_b64 v106, v[198:199] offset:16640
	v_cvt_pk_bf16_f32 v202, v202, v203
	v_cvt_pk_bf16_f32 v203, v204, v205
	v_cvt_pk_bf16_f32 v206, v206, v207
	v_cvt_pk_bf16_f32 v207, v208, v209
	ds_write_b64 v106, v[206:207] offset:32
	v_cvt_pk_bf16_f32 v210, v210, v211
	v_cvt_pk_bf16_f32 v211, v212, v213
	ds_write_b64 v106, v[210:211] offset:16672
	v_cvt_pk_bf16_f32 v214, v214, v215
	v_cvt_pk_bf16_f32 v215, v216, v217
	v_cvt_pk_bf16_f32 v218, v218, v219
	v_cvt_pk_bf16_f32 v219, v220, v221
	ds_write_b64 v106, v[218:219] offset:64
	v_cvt_pk_bf16_f32 v222, v222, v223
	v_cvt_pk_bf16_f32 v223, v224, v225
	ds_write_b64 v106, v[222:223] offset:16704
	v_cvt_pk_bf16_f32 v226, v226, v227
	v_cvt_pk_bf16_f32 v227, v228, v229
	v_cvt_pk_bf16_f32 v230, v230, v231
	v_cvt_pk_bf16_f32 v231, v232, v233
	ds_write_b64 v106, v[230:231] offset:96
	v_cvt_pk_bf16_f32 v132, v132, v133
	v_cvt_pk_bf16_f32 v133, v134, v135
	ds_write_b64 v106, v[132:133] offset:16736
	v_cvt_pk_bf16_f32 v136, v136, v137
	v_cvt_pk_bf16_f32 v137, v138, v139
	s_and_saveexec_b64 s[22:23], s[8:9]
	ds_write_b64 v107, v[202:203]
	ds_write_b64 v107, v[214:215] offset:32
	ds_write_b64 v107, v[226:227] offset:64
	ds_write_b64 v107, v[136:137] offset:96
	s_branch .LBB0_790
